# v25: v23 + the position of the cache-panel conversion among the input-projection units is chosen per XCD (bid mod 8, 7 positions) instead of per group of 8 workgroups
# speedup vs baseline: 1.0154x; 1.0154x over previous
.LBB0_434:
	s_cmp_lt_i32 s96, 4
	s_cselect_b64 s[4:5], -1, 0
	v_writelane_b32 v238, s87, 4
	s_and_b64 s[0:1], s[4:5], s[0:1]
	v_writelane_b32 v238, s96, 5
	s_andn2_b64 vcc, exec, s[0:1]
	s_nop 0
	v_writelane_b32 v238, s97, 6
	v_writelane_b32 v238, s84, 7
	s_cbranch_vccnz .LBB0_846
	s_and_b32 s0, s94, 7
	s_cmp_eq_u32 s0, 7
	s_cselect_b32 s44, 0, s0
	s_cmp_lt_i32 s44, 1
	s_cselect_b64 s[0:1], -1, 0
	s_cmpk_gt_i32 s94, 0x58a
	s_cselect_b64 s[2:3], -1, 0
	s_or_b64 s[2:3], s[2:3], s[0:1]
	s_and_b64 vcc, exec, s[2:3]
	s_cbranch_vccnz .LBB0_441
	s_ashr_i32 s0, s94, 31
	s_lshr_b32 s0, s0, 29
	s_add_i32 s6, s94, s0
	s_and_b32 s0, s6, -8
	s_sub_i32 s7, s94, s0
	s_cmp_gt_i32 s7, 2
	s_cbranch_scc0 .LBB0_438
	s_mul_i32 s0, s7, 0xb1
	s_add_i32 s8, s0, 3
	s_cbranch_execz .LBB0_439
	s_branch .LBB0_440
